# scan: fast-path global loads with per-thread running addresses, operand prefetch across the half boundary, X-init MFMA chain issued before the cross-lane substitution terms
# speedup vs baseline: 1.0090x; 1.0006x over previous
.Lmy_ck_nz:
	s_mov_b32 s100, 0xe000
	s_cmp_eq_u32 s23, 0
	s_cselect_b32 s100, 0x1c000, s100
	v_lshl_add_u32 v236, v224, 4, s100
	v_xor_b32_e32 v225, v224, v234
	v_lshl_add_u32 v225, v225, 4, s100
	s_add_i32 s101, s100, 0x2000
	v_lshl_add_u32 v226, v234, 4, s101
	s_add_i32 s101, s100, 0x2600
	v_mov_b32_e32 v72, s101
	v_cmp_eq_u32_e64 s[96:97], 0, v234
	s_add_i32 s101, s100, 0x2500
	v_mov_b32_e32 v73, s101
	s_add_i32 s101, s100, 0x2510
	v_mov_b32_e32 v74, s101
	v_cndmask_b32_e64 v227, v72, v73, s[96:97]
	v_cmp_eq_u32_e64 s[96:97], 1, v234
	s_add_i32 s101, s100, 0x2590
	v_mov_b32_e32 v75, s101
	v_and_b32_e32 v76, 1, v234
	v_cndmask_b32_e64 v228, v72, v74, s[96:97]
	v_cndmask_b32_e64 v229, v72, v75, s[96:97]
	v_lshlrev_b32_e32 v76, 10, v76
	v_lshl_add_u32 v76, v233, 2, v76
	v_add_u32_e32 v76, s62, v76
	s_lshl_b32 s96, s23, 13
	s_add_i32 s96, s96, 0xa000
	v_add_u32_e32 v230, s96, v76
	s_lshl_b32 s96, s23, 13
	s_add_i32 s96, s96, 0x18000
	v_add_u32_e32 v231, s96, v76
	v_add_u32_e32 v232, 48, v224
	v_and_b32_e32 v232, 63, v232
	v_lshlrev_b32_e32 v232, 2, v232
	s_mov_b32 s100, 0x6100
	s_cmp_eq_u32 s23, 0
	s_cselect_b32 s100, s100, 0x4e00
	v_add_u32_e32 v26, s100, v225
	v_add_u32_e32 v27, s100, v236
	v_add_u32_e32 v28, s100, v226
	v_add_u32_e32 v29, s100, v227
	v_add_u32_e32 v30, s100, v228
	v_add_u32_e32 v31, s100, v229
	ds_read_b128 v[80:83], v225 offset:8448
	ds_read_b32 v84, v230
	ds_read_b32 v85, v230 offset:256
	ds_read_b32 v86, v230 offset:512
	ds_read_b32 v87, v230 offset:768
	ds_read_b128 v[88:91], v225
	ds_read_b128 v[92:95], v225 offset:1024
	ds_read_b128 v[96:99], v225 offset:2048
	ds_read_b128 v[100:103], v225 offset:3072
	ds_read_b32 v104, v227 offset:4
	ds_read_b32 v105, v227 offset:76
	ds_read_b64 v[106:107], v227 offset:8
	ds_read_b64 v[108:109], v227 offset:40
	ds_read_b32 v126, v229 offset:4
	ds_read_b32 v127, v229 offset:76
	ds_read_b64 v[128:129], v229 offset:8
	ds_read_b64 v[130:131], v229 offset:40
	ds_read_b64 v[110:111], v228
	ds_read_b64 v[112:113], v228 offset:32
	ds_read_b64 v[114:115], v228 offset:64
	ds_read_b64 v[116:117], v228 offset:96
	ds_read_b64 v[118:119], v228 offset:8
	ds_read_b64 v[120:121], v228 offset:40
	ds_read_b64 v[122:123], v228 offset:72
	ds_read_b64 v[124:125], v228 offset:104
	s_waitcnt lgkmcnt(15)
	v_cndmask_b32_e64 v76, 0, v84, s[98:99]
	v_cndmask_b32_e64 v77, 0, v85, s[98:99]
	v_cndmask_b32_e64 v78, 0, v86, s[98:99]
	v_cndmask_b32_e64 v79, 0, v87, s[98:99]
	v_mfma_f32_16x16x4_f32 v[240:243], v80, v76, 0
	v_mfma_f32_16x16x4_f32 v[240:243], v81, v77, v[240:243]
	v_mfma_f32_16x16x4_f32 v[240:243], v82, v78, v[240:243]
	v_mfma_f32_16x16x4_f32 v[240:243], v83, v79, v[240:243]
	v_mfma_f32_16x16x4_f32 v[240:243], v88, v208, v[240:243]
	ds_read_b128 v[184:187], v236 offset:4096
	ds_read_b128 v[188:191], v236 offset:5120
	v_mfma_f32_16x16x4_f32 v[244:247], v89, v209, 0
	ds_read_b128 v[192:195], v236 offset:6144
	ds_read_b128 v[196:199], v236 offset:7168
	v_mfma_f32_16x16x4_f32 v[240:243], v90, v210, v[240:243]
	ds_read_b128 v[132:135], v225 offset:18432
	ds_read_b32 v136, v230 offset:2048
	v_mfma_f32_16x16x4_f32 v[244:247], v91, v211, v[244:247]
	ds_read_b32 v137, v230 offset:2304
	ds_read_b32 v138, v230 offset:2560
	v_mfma_f32_16x16x4_f32 v[240:243], v92, v212, v[240:243]
	ds_read_b32 v139, v230 offset:2816
	ds_read_b128 v[140:143], v225 offset:9984
	v_mfma_f32_16x16x4_f32 v[244:247], v93, v213, v[244:247]
	ds_read_b128 v[144:147], v225 offset:11008
	ds_read_b128 v[148:151], v225 offset:12032
	v_mfma_f32_16x16x4_f32 v[240:243], v94, v214, v[240:243]
	ds_read_b128 v[152:155], v225 offset:13056
	ds_read_b32 v156, v227 offset:9988
	v_mfma_f32_16x16x4_f32 v[244:247], v95, v215, v[244:247]
	ds_read_b32 v157, v227 offset:10060
	ds_read_b64 v[158:159], v227 offset:9992
	v_mfma_f32_16x16x4_f32 v[240:243], v96, v216, v[240:243]
	ds_read_b64 v[160:161], v227 offset:10024
	ds_read_b32 v178, v229 offset:9988
	v_mfma_f32_16x16x4_f32 v[244:247], v97, v217, v[244:247]
	ds_read_b32 v179, v229 offset:10060
	ds_read_b64 v[180:181], v229 offset:9992
	v_mfma_f32_16x16x4_f32 v[240:243], v98, v218, v[240:243]
	ds_read_b64 v[182:183], v229 offset:10024
	ds_read_b64 v[162:163], v228 offset:9984
	v_mfma_f32_16x16x4_f32 v[244:247], v99, v219, v[244:247]
	ds_read_b64 v[164:165], v228 offset:10016
	ds_read_b64 v[166:167], v228 offset:10048
	v_mfma_f32_16x16x4_f32 v[240:243], v100, v220, v[240:243]
	ds_read_b64 v[168:169], v228 offset:10080
	ds_read_b64 v[170:171], v228 offset:9992
	v_mfma_f32_16x16x4_f32 v[244:247], v101, v221, v[244:247]
	ds_read_b64 v[172:173], v228 offset:10024
	ds_read_b64 v[174:175], v228 offset:10056
	v_mfma_f32_16x16x4_f32 v[240:243], v102, v222, v[240:243]
	ds_read_b64 v[176:177], v228 offset:10088
	v_mfma_f32_16x16x4_f32 v[244:247], v103, v223, v[244:247]
	s_nop 9
	v_pk_add_f32 v[240:241], v[240:241], v[244:245]
	v_pk_add_f32 v[242:243], v[242:243], v[246:247]
	v_fmac_f32_e32 v241, v104, v240
	s_waitcnt lgkmcnt(15)
	v_pk_fma_f32 v[242:243], v[106:107], v[240:241], v[242:243] op_sel:[0,0,0] op_sel_hi:[1,0,1]
	v_pk_fma_f32 v[242:243], v[108:109], v[240:241], v[242:243] op_sel:[0,1,0] op_sel_hi:[1,1,1]
	v_fmac_f32_e32 v243, v105, v242
	ds_bpermute_b32 v204, v232, v240
	ds_bpermute_b32 v205, v232, v241
	ds_bpermute_b32 v206, v232, v242
	ds_bpermute_b32 v207, v232, v243
	ds_read_b128 v[88:91], v226
	ds_read_b128 v[92:95], v226 offset:64
	ds_read_b128 v[96:99], v226 offset:128
	ds_read_b128 v[100:103], v226 offset:192
	v_cndmask_b32_e64 v76, 0, v136, s[98:99]
	v_cndmask_b32_e64 v77, 0, v137, s[98:99]
	v_cndmask_b32_e64 v78, 0, v138, s[98:99]
	v_cndmask_b32_e64 v79, 0, v139, s[98:99]
	v_mfma_f32_16x16x4_f32 v[72:75], v132, v76, 0
	v_mfma_f32_16x16x4_f32 v[72:75], v133, v77, v[72:75]
	v_mfma_f32_16x16x4_f32 v[72:75], v134, v78, v[72:75]
	v_mfma_f32_16x16x4_f32 v[72:75], v135, v79, v[72:75]
	s_waitcnt lgkmcnt(6)
	v_pk_fma_f32 v[240:241], v[110:111], v[204:205], v[240:241] op_sel:[0,0,0] op_sel_hi:[1,0,1]
	v_pk_fma_f32 v[240:241], v[112:113], v[204:205], v[240:241] op_sel:[0,1,0] op_sel_hi:[1,1,1]
	s_waitcnt lgkmcnt(4)
	v_pk_fma_f32 v[240:241], v[114:115], v[206:207], v[240:241] op_sel:[0,0,0] op_sel_hi:[1,0,1]
	v_pk_fma_f32 v[240:241], v[116:117], v[206:207], v[240:241] op_sel:[0,1,0] op_sel_hi:[1,1,1]
	v_pk_fma_f32 v[242:243], v[118:119], v[204:205], v[242:243] op_sel:[0,0,0] op_sel_hi:[1,0,1]
	v_pk_fma_f32 v[242:243], v[120:121], v[204:205], v[242:243] op_sel:[0,1,0] op_sel_hi:[1,1,1]
	v_pk_fma_f32 v[242:243], v[122:123], v[206:207], v[242:243] op_sel:[0,0,0] op_sel_hi:[1,0,1]
	v_pk_fma_f32 v[242:243], v[124:125], v[206:207], v[242:243] op_sel:[0,1,0] op_sel_hi:[1,1,1]
	v_fmac_f32_e32 v241, v126, v240
	v_pk_fma_f32 v[242:243], v[128:129], v[240:241], v[242:243] op_sel:[0,0,0] op_sel_hi:[1,0,1]
	v_pk_fma_f32 v[242:243], v[130:131], v[240:241], v[242:243] op_sel:[0,1,0] op_sel_hi:[1,1,1]
	v_fmac_f32_e32 v243, v127, v242
	v_cndmask_b32_e64 v200, v240, v84, s[98:99]
	v_cndmask_b32_e64 v201, v241, v85, s[98:99]
	v_cndmask_b32_e64 v202, v242, v86, s[98:99]
	v_cndmask_b32_e64 v203, v243, v87, s[98:99]
	v_cndmask_b32_e64 v252, v240, 0, s[98:99]
	v_cndmask_b32_e64 v253, v241, 0, s[98:99]
	v_cndmask_b32_e64 v254, v242, 0, s[98:99]
	v_cndmask_b32_e64 v255, v243, 0, s[98:99]
	v_mfma_f32_16x16x4_f32 v[208:211], v184, v200, v[208:211]
	v_mfma_f32_16x16x4_f32 v[212:215], v188, v200, v[212:215]
	v_mfma_f32_16x16x4_f32 v[216:219], v192, v200, v[216:219]
	v_mfma_f32_16x16x4_f32 v[220:223], v196, v200, v[220:223]
	v_mfma_f32_16x16x4_f32 v[208:211], v185, v201, v[208:211]
	v_mfma_f32_16x16x4_f32 v[212:215], v189, v201, v[212:215]
	v_mfma_f32_16x16x4_f32 v[216:219], v193, v201, v[216:219]
	v_mfma_f32_16x16x4_f32 v[220:223], v197, v201, v[220:223]
	v_mfma_f32_16x16x4_f32 v[208:211], v186, v202, v[208:211]
	v_mfma_f32_16x16x4_f32 v[212:215], v190, v202, v[212:215]
	v_mfma_f32_16x16x4_f32 v[216:219], v194, v202, v[216:219]
	v_mfma_f32_16x16x4_f32 v[220:223], v198, v202, v[220:223]
	v_mfma_f32_16x16x4_f32 v[208:211], v187, v203, v[208:211]
	v_mfma_f32_16x16x4_f32 v[212:215], v191, v203, v[212:215]
	v_mfma_f32_16x16x4_f32 v[216:219], v195, v203, v[216:219]
	v_mfma_f32_16x16x4_f32 v[220:223], v199, v203, v[220:223]
	v_mfma_f32_16x16x4_f32 v[248:251], v80, v252, v[240:243]
	v_mfma_f32_16x16x4_f32 v[248:251], v81, v253, v[248:251]
	v_mfma_f32_16x16x4_f32 v[248:251], v82, v254, v[248:251]
	v_mfma_f32_16x16x4_f32 v[248:251], v83, v255, v[248:251]
	s_waitcnt lgkmcnt(3)
	s_nop 2
	v_pk_mul_f32 v[208:209], v[208:209], v[88:89]
	v_pk_mul_f32 v[210:211], v[210:211], v[90:91]
	s_nop 0
	v_mfma_f32_16x16x4_f32 v[72:75], v140, v208, v[72:75]
	s_waitcnt lgkmcnt(2)
	v_pk_mul_f32 v[212:213], v[212:213], v[92:93]
	v_mfma_f32_16x16x4_f32 v[244:247], v141, v209, 0
	v_pk_mul_f32 v[214:215], v[214:215], v[94:95]
	v_mfma_f32_16x16x4_f32 v[72:75], v142, v210, v[72:75]
	s_waitcnt lgkmcnt(1)
	v_pk_mul_f32 v[216:217], v[216:217], v[96:97]
	v_mfma_f32_16x16x4_f32 v[244:247], v143, v211, v[244:247]
	v_pk_mul_f32 v[218:219], v[218:219], v[98:99]
	v_mfma_f32_16x16x4_f32 v[72:75], v144, v212, v[72:75]
	s_waitcnt lgkmcnt(0)
	v_pk_mul_f32 v[220:221], v[220:221], v[100:101]
	v_mfma_f32_16x16x4_f32 v[244:247], v145, v213, v[244:247]
	v_pk_mul_f32 v[222:223], v[222:223], v[102:103]
	v_mfma_f32_16x16x4_f32 v[72:75], v146, v214, v[72:75]
	s_mov_b64 exec, s[98:99]
	ds_write_b32 v231, v248
	ds_write_b32 v231, v249 offset:256
	ds_write_b32 v231, v250 offset:512
	ds_write_b32 v231, v251 offset:768
	s_mov_b64 exec, -1
	ds_read_b128 v[184:187], v236 offset:14080
	ds_read_b128 v[188:191], v236 offset:15104
	v_mfma_f32_16x16x4_f32 v[244:247], v147, v215, v[244:247]
	ds_read_b128 v[192:195], v236 offset:16128
	ds_read_b128 v[196:199], v236 offset:17152
	v_mfma_f32_16x16x4_f32 v[72:75], v148, v216, v[72:75]
	ds_read_b128 v[80:83], v26 offset:8448
	ds_read_b32 v84, v230 offset:4096
	ds_read_b32 v85, v230 offset:4352
	ds_read_b32 v86, v230 offset:4608
	v_mfma_f32_16x16x4_f32 v[244:247], v149, v217, v[244:247]
	ds_read_b32 v87, v230 offset:4864
	ds_read_b128 v[88:91], v26
	ds_read_b128 v[92:95], v26 offset:1024
	ds_read_b128 v[96:99], v26 offset:2048
	v_mfma_f32_16x16x4_f32 v[72:75], v150, v218, v[72:75]
	ds_read_b128 v[100:103], v26 offset:3072
	ds_read_b32 v104, v29 offset:4
	ds_read_b32 v105, v29 offset:76
	ds_read_b64 v[106:107], v29 offset:8
	v_mfma_f32_16x16x4_f32 v[244:247], v151, v219, v[244:247]
	ds_read_b64 v[108:109], v29 offset:40
	ds_read_b32 v126, v31 offset:4
	ds_read_b32 v127, v31 offset:76
	ds_read_b64 v[128:129], v31 offset:8
	v_mfma_f32_16x16x4_f32 v[72:75], v152, v220, v[72:75]
	ds_read_b64 v[130:131], v31 offset:40
	ds_read_b64 v[110:111], v30
	ds_read_b64 v[112:113], v30 offset:32
	ds_read_b64 v[114:115], v30 offset:64
	v_mfma_f32_16x16x4_f32 v[244:247], v153, v221, v[244:247]
	ds_read_b64 v[116:117], v30 offset:96
	ds_read_b64 v[118:119], v30 offset:8
	ds_read_b64 v[120:121], v30 offset:40
	ds_read_b64 v[122:123], v30 offset:72
	v_mfma_f32_16x16x4_f32 v[72:75], v154, v222, v[72:75]
	ds_read_b64 v[124:125], v30 offset:104
	v_mfma_f32_16x16x4_f32 v[244:247], v155, v223, v[244:247]
	s_nop 9
	v_pk_add_f32 v[72:73], v[72:73], v[244:245]
	v_pk_add_f32 v[74:75], v[74:75], v[246:247]
	v_fmac_f32_e32 v73, v156, v72
	v_pk_fma_f32 v[74:75], v[158:159], v[72:73], v[74:75] op_sel:[0,0,0] op_sel_hi:[1,0,1]
	v_pk_fma_f32 v[74:75], v[160:161], v[72:73], v[74:75] op_sel:[0,1,0] op_sel_hi:[1,1,1]
	v_fmac_f32_e32 v75, v157, v74
	ds_bpermute_b32 v204, v232, v72
	ds_bpermute_b32 v205, v232, v73
	ds_bpermute_b32 v206, v232, v74
	ds_bpermute_b32 v207, v232, v75
	ds_read_b128 v[140:143], v226 offset:9984
	ds_read_b128 v[144:147], v226 offset:10048
	ds_read_b128 v[148:151], v226 offset:10112
	ds_read_b128 v[152:155], v226 offset:10176
	s_waitcnt lgkmcnt(15)
	v_cndmask_b32_e64 v76, 0, v84, s[98:99]
	v_cndmask_b32_e64 v77, 0, v85, s[98:99]
	v_cndmask_b32_e64 v78, 0, v86, s[98:99]
	v_cndmask_b32_e64 v79, 0, v87, s[98:99]
	v_mfma_f32_16x16x4_f32 v[240:243], v80, v76, 0
	v_mfma_f32_16x16x4_f32 v[240:243], v81, v77, v[240:243]
	v_mfma_f32_16x16x4_f32 v[240:243], v82, v78, v[240:243]
	v_mfma_f32_16x16x4_f32 v[240:243], v83, v79, v[240:243]
	s_waitcnt lgkmcnt(6)
	v_pk_fma_f32 v[72:73], v[162:163], v[204:205], v[72:73] op_sel:[0,0,0] op_sel_hi:[1,0,1]
	v_pk_fma_f32 v[72:73], v[164:165], v[204:205], v[72:73] op_sel:[0,1,0] op_sel_hi:[1,1,1]
	s_waitcnt lgkmcnt(4)
	v_pk_fma_f32 v[72:73], v[166:167], v[206:207], v[72:73] op_sel:[0,0,0] op_sel_hi:[1,0,1]
	v_pk_fma_f32 v[72:73], v[168:169], v[206:207], v[72:73] op_sel:[0,1,0] op_sel_hi:[1,1,1]
	v_pk_fma_f32 v[74:75], v[170:171], v[204:205], v[74:75] op_sel:[0,0,0] op_sel_hi:[1,0,1]
	v_pk_fma_f32 v[74:75], v[172:173], v[204:205], v[74:75] op_sel:[0,1,0] op_sel_hi:[1,1,1]
	v_pk_fma_f32 v[74:75], v[174:175], v[206:207], v[74:75] op_sel:[0,0,0] op_sel_hi:[1,0,1]
	v_pk_fma_f32 v[74:75], v[176:177], v[206:207], v[74:75] op_sel:[0,1,0] op_sel_hi:[1,1,1]
	v_fmac_f32_e32 v73, v178, v72
	v_pk_fma_f32 v[74:75], v[180:181], v[72:73], v[74:75] op_sel:[0,0,0] op_sel_hi:[1,0,1]
	v_pk_fma_f32 v[74:75], v[182:183], v[72:73], v[74:75] op_sel:[0,1,0] op_sel_hi:[1,1,1]
	v_fmac_f32_e32 v75, v179, v74
	v_cndmask_b32_e64 v200, v72, v136, s[98:99]
	v_cndmask_b32_e64 v201, v73, v137, s[98:99]
	v_cndmask_b32_e64 v202, v74, v138, s[98:99]
	v_cndmask_b32_e64 v203, v75, v139, s[98:99]
	v_cndmask_b32_e64 v252, v72, 0, s[98:99]
	v_cndmask_b32_e64 v253, v73, 0, s[98:99]
	v_cndmask_b32_e64 v254, v74, 0, s[98:99]
	v_cndmask_b32_e64 v255, v75, 0, s[98:99]
	v_mfma_f32_16x16x4_f32 v[208:211], v184, v200, v[208:211]
	v_mfma_f32_16x16x4_f32 v[212:215], v188, v200, v[212:215]
	v_mfma_f32_16x16x4_f32 v[216:219], v192, v200, v[216:219]
	v_mfma_f32_16x16x4_f32 v[220:223], v196, v200, v[220:223]
	v_mfma_f32_16x16x4_f32 v[208:211], v185, v201, v[208:211]
	v_mfma_f32_16x16x4_f32 v[212:215], v189, v201, v[212:215]
	v_mfma_f32_16x16x4_f32 v[216:219], v193, v201, v[216:219]
	v_mfma_f32_16x16x4_f32 v[220:223], v197, v201, v[220:223]
	v_mfma_f32_16x16x4_f32 v[208:211], v186, v202, v[208:211]
	v_mfma_f32_16x16x4_f32 v[212:215], v190, v202, v[212:215]
	v_mfma_f32_16x16x4_f32 v[216:219], v194, v202, v[216:219]
	v_mfma_f32_16x16x4_f32 v[220:223], v198, v202, v[220:223]
	v_mfma_f32_16x16x4_f32 v[208:211], v187, v203, v[208:211]
	v_mfma_f32_16x16x4_f32 v[212:215], v191, v203, v[212:215]
	v_mfma_f32_16x16x4_f32 v[216:219], v195, v203, v[216:219]
	v_mfma_f32_16x16x4_f32 v[220:223], v199, v203, v[220:223]
	v_mfma_f32_16x16x4_f32 v[248:251], v132, v252, v[72:75]
	v_mfma_f32_16x16x4_f32 v[248:251], v133, v253, v[248:251]
	v_mfma_f32_16x16x4_f32 v[248:251], v134, v254, v[248:251]
	v_mfma_f32_16x16x4_f32 v[248:251], v135, v255, v[248:251]
	s_waitcnt lgkmcnt(3)
	s_nop 2
	v_pk_mul_f32 v[208:209], v[208:209], v[140:141]
	v_pk_mul_f32 v[210:211], v[210:211], v[142:143]
	s_nop 0
	v_mfma_f32_16x16x4_f32 v[240:243], v88, v208, v[240:243]
	s_waitcnt lgkmcnt(2)
	v_pk_mul_f32 v[212:213], v[212:213], v[144:145]
	v_mfma_f32_16x16x4_f32 v[244:247], v89, v209, 0
	v_pk_mul_f32 v[214:215], v[214:215], v[146:147]
	v_mfma_f32_16x16x4_f32 v[240:243], v90, v210, v[240:243]
	s_waitcnt lgkmcnt(1)
	v_pk_mul_f32 v[216:217], v[216:217], v[148:149]
	v_mfma_f32_16x16x4_f32 v[244:247], v91, v211, v[244:247]
	v_pk_mul_f32 v[218:219], v[218:219], v[150:151]
	v_mfma_f32_16x16x4_f32 v[240:243], v92, v212, v[240:243]
	s_waitcnt lgkmcnt(0)
	v_pk_mul_f32 v[220:221], v[220:221], v[152:153]
	v_mfma_f32_16x16x4_f32 v[244:247], v93, v213, v[244:247]
	v_pk_mul_f32 v[222:223], v[222:223], v[154:155]
	v_mfma_f32_16x16x4_f32 v[240:243], v94, v214, v[240:243]
	s_mov_b64 exec, s[98:99]
	ds_write_b32 v231, v248 offset:2048
	ds_write_b32 v231, v249 offset:2304
	ds_write_b32 v231, v250 offset:2560
	ds_write_b32 v231, v251 offset:2816
	s_mov_b64 exec, -1
	ds_read_b128 v[184:187], v27 offset:4096
	ds_read_b128 v[188:191], v27 offset:5120
	v_mfma_f32_16x16x4_f32 v[244:247], v95, v215, v[244:247]
	ds_read_b128 v[192:195], v27 offset:6144
	ds_read_b128 v[196:199], v27 offset:7168
	v_mfma_f32_16x16x4_f32 v[240:243], v96, v216, v[240:243]
	ds_read_b128 v[132:135], v26 offset:18432
	ds_read_b32 v136, v230 offset:6144
	ds_read_b32 v137, v230 offset:6400
	ds_read_b32 v138, v230 offset:6656
	v_mfma_f32_16x16x4_f32 v[244:247], v97, v217, v[244:247]
	ds_read_b32 v139, v230 offset:6912
	ds_read_b128 v[140:143], v26 offset:9984
	ds_read_b128 v[144:147], v26 offset:11008
	ds_read_b128 v[148:151], v26 offset:12032
	v_mfma_f32_16x16x4_f32 v[240:243], v98, v218, v[240:243]
	ds_read_b128 v[152:155], v26 offset:13056
	ds_read_b32 v156, v29 offset:9988
	ds_read_b32 v157, v29 offset:10060
	ds_read_b64 v[158:159], v29 offset:9992
	v_mfma_f32_16x16x4_f32 v[244:247], v99, v219, v[244:247]
	ds_read_b64 v[160:161], v29 offset:10024
	ds_read_b32 v178, v31 offset:9988
	ds_read_b32 v179, v31 offset:10060
	ds_read_b64 v[180:181], v31 offset:9992
	v_mfma_f32_16x16x4_f32 v[240:243], v100, v220, v[240:243]
	ds_read_b64 v[182:183], v31 offset:10024
	ds_read_b64 v[162:163], v30 offset:9984
	ds_read_b64 v[164:165], v30 offset:10016
	ds_read_b64 v[166:167], v30 offset:10048
	v_mfma_f32_16x16x4_f32 v[244:247], v101, v221, v[244:247]
	ds_read_b64 v[168:169], v30 offset:10080
	ds_read_b64 v[170:171], v30 offset:9992
	ds_read_b64 v[172:173], v30 offset:10024
	ds_read_b64 v[174:175], v30 offset:10056
	v_mfma_f32_16x16x4_f32 v[240:243], v102, v222, v[240:243]
	ds_read_b64 v[176:177], v30 offset:10088
	v_mfma_f32_16x16x4_f32 v[244:247], v103, v223, v[244:247]
	s_nop 9
	v_pk_add_f32 v[240:241], v[240:241], v[244:245]
	v_pk_add_f32 v[242:243], v[242:243], v[246:247]
	v_fmac_f32_e32 v241, v104, v240
	v_pk_fma_f32 v[242:243], v[106:107], v[240:241], v[242:243] op_sel:[0,0,0] op_sel_hi:[1,0,1]
	v_pk_fma_f32 v[242:243], v[108:109], v[240:241], v[242:243] op_sel:[0,1,0] op_sel_hi:[1,1,1]
	v_fmac_f32_e32 v243, v105, v242
	ds_bpermute_b32 v204, v232, v240
	ds_bpermute_b32 v205, v232, v241
	ds_bpermute_b32 v206, v232, v242
	ds_bpermute_b32 v207, v232, v243
	ds_read_b128 v[88:91], v28
	ds_read_b128 v[92:95], v28 offset:64
	ds_read_b128 v[96:99], v28 offset:128
	ds_read_b128 v[100:103], v28 offset:192
	s_waitcnt lgkmcnt(15)
	v_cndmask_b32_e64 v76, 0, v136, s[98:99]
	v_cndmask_b32_e64 v77, 0, v137, s[98:99]
	v_cndmask_b32_e64 v78, 0, v138, s[98:99]
	v_cndmask_b32_e64 v79, 0, v139, s[98:99]
	v_mfma_f32_16x16x4_f32 v[72:75], v132, v76, 0
	v_mfma_f32_16x16x4_f32 v[72:75], v133, v77, v[72:75]
	v_mfma_f32_16x16x4_f32 v[72:75], v134, v78, v[72:75]
	v_mfma_f32_16x16x4_f32 v[72:75], v135, v79, v[72:75]
	s_waitcnt lgkmcnt(6)
	v_pk_fma_f32 v[240:241], v[110:111], v[204:205], v[240:241] op_sel:[0,0,0] op_sel_hi:[1,0,1]
	v_pk_fma_f32 v[240:241], v[112:113], v[204:205], v[240:241] op_sel:[0,1,0] op_sel_hi:[1,1,1]
	s_waitcnt lgkmcnt(4)
	v_pk_fma_f32 v[240:241], v[114:115], v[206:207], v[240:241] op_sel:[0,0,0] op_sel_hi:[1,0,1]
	v_pk_fma_f32 v[240:241], v[116:117], v[206:207], v[240:241] op_sel:[0,1,0] op_sel_hi:[1,1,1]
	v_pk_fma_f32 v[242:243], v[118:119], v[204:205], v[242:243] op_sel:[0,0,0] op_sel_hi:[1,0,1]
	v_pk_fma_f32 v[242:243], v[120:121], v[204:205], v[242:243] op_sel:[0,1,0] op_sel_hi:[1,1,1]
	v_pk_fma_f32 v[242:243], v[122:123], v[206:207], v[242:243] op_sel:[0,0,0] op_sel_hi:[1,0,1]
	v_pk_fma_f32 v[242:243], v[124:125], v[206:207], v[242:243] op_sel:[0,1,0] op_sel_hi:[1,1,1]
	v_fmac_f32_e32 v241, v126, v240
	v_pk_fma_f32 v[242:243], v[128:129], v[240:241], v[242:243] op_sel:[0,0,0] op_sel_hi:[1,0,1]
	v_pk_fma_f32 v[242:243], v[130:131], v[240:241], v[242:243] op_sel:[0,1,0] op_sel_hi:[1,1,1]
	v_fmac_f32_e32 v243, v127, v242
	v_cndmask_b32_e64 v200, v240, v84, s[98:99]
	v_cndmask_b32_e64 v201, v241, v85, s[98:99]
	v_cndmask_b32_e64 v202, v242, v86, s[98:99]
	v_cndmask_b32_e64 v203, v243, v87, s[98:99]
	v_cndmask_b32_e64 v252, v240, 0, s[98:99]
	v_cndmask_b32_e64 v253, v241, 0, s[98:99]
	v_cndmask_b32_e64 v254, v242, 0, s[98:99]
	v_cndmask_b32_e64 v255, v243, 0, s[98:99]
	v_mfma_f32_16x16x4_f32 v[208:211], v184, v200, v[208:211]
	v_mfma_f32_16x16x4_f32 v[212:215], v188, v200, v[212:215]
	v_mfma_f32_16x16x4_f32 v[216:219], v192, v200, v[216:219]
	v_mfma_f32_16x16x4_f32 v[220:223], v196, v200, v[220:223]
	v_mfma_f32_16x16x4_f32 v[208:211], v185, v201, v[208:211]
	v_mfma_f32_16x16x4_f32 v[212:215], v189, v201, v[212:215]
	v_mfma_f32_16x16x4_f32 v[216:219], v193, v201, v[216:219]
	v_mfma_f32_16x16x4_f32 v[220:223], v197, v201, v[220:223]
	v_mfma_f32_16x16x4_f32 v[208:211], v186, v202, v[208:211]
	v_mfma_f32_16x16x4_f32 v[212:215], v190, v202, v[212:215]
	v_mfma_f32_16x16x4_f32 v[216:219], v194, v202, v[216:219]
	v_mfma_f32_16x16x4_f32 v[220:223], v198, v202, v[220:223]
	v_mfma_f32_16x16x4_f32 v[208:211], v187, v203, v[208:211]
	v_mfma_f32_16x16x4_f32 v[212:215], v191, v203, v[212:215]
	v_mfma_f32_16x16x4_f32 v[216:219], v195, v203, v[216:219]
	v_mfma_f32_16x16x4_f32 v[220:223], v199, v203, v[220:223]
	v_mfma_f32_16x16x4_f32 v[248:251], v80, v252, v[240:243]
	v_mfma_f32_16x16x4_f32 v[248:251], v81, v253, v[248:251]
	v_mfma_f32_16x16x4_f32 v[248:251], v82, v254, v[248:251]
	v_mfma_f32_16x16x4_f32 v[248:251], v83, v255, v[248:251]
	s_waitcnt lgkmcnt(3)
	s_nop 2
	v_pk_mul_f32 v[208:209], v[208:209], v[88:89]
	v_pk_mul_f32 v[210:211], v[210:211], v[90:91]
	s_nop 0
	v_mfma_f32_16x16x4_f32 v[72:75], v140, v208, v[72:75]
	s_waitcnt lgkmcnt(2)
	v_pk_mul_f32 v[212:213], v[212:213], v[92:93]
	v_mfma_f32_16x16x4_f32 v[244:247], v141, v209, 0
	v_pk_mul_f32 v[214:215], v[214:215], v[94:95]
	v_mfma_f32_16x16x4_f32 v[72:75], v142, v210, v[72:75]
	s_waitcnt lgkmcnt(1)
	v_pk_mul_f32 v[216:217], v[216:217], v[96:97]
	v_mfma_f32_16x16x4_f32 v[244:247], v143, v211, v[244:247]
	v_pk_mul_f32 v[218:219], v[218:219], v[98:99]
	v_mfma_f32_16x16x4_f32 v[72:75], v144, v212, v[72:75]
	s_waitcnt lgkmcnt(0)
	v_pk_mul_f32 v[220:221], v[220:221], v[100:101]
	v_mfma_f32_16x16x4_f32 v[244:247], v145, v213, v[244:247]
	v_pk_mul_f32 v[222:223], v[222:223], v[102:103]
	v_mfma_f32_16x16x4_f32 v[72:75], v146, v214, v[72:75]
	s_mov_b64 exec, s[98:99]
	ds_write_b32 v231, v248 offset:4096
	ds_write_b32 v231, v249 offset:4352
	ds_write_b32 v231, v250 offset:4608
	ds_write_b32 v231, v251 offset:4864
	s_mov_b64 exec, -1
	ds_read_b128 v[184:187], v27 offset:14080
	ds_read_b128 v[188:191], v27 offset:15104
	v_mfma_f32_16x16x4_f32 v[244:247], v147, v215, v[244:247]
	ds_read_b128 v[192:195], v27 offset:16128
	ds_read_b128 v[196:199], v27 offset:17152
	v_mfma_f32_16x16x4_f32 v[72:75], v148, v216, v[72:75]
	v_mfma_f32_16x16x4_f32 v[244:247], v149, v217, v[244:247]
	v_mfma_f32_16x16x4_f32 v[72:75], v150, v218, v[72:75]
	v_mfma_f32_16x16x4_f32 v[244:247], v151, v219, v[244:247]
	v_mfma_f32_16x16x4_f32 v[72:75], v152, v220, v[72:75]
	v_mfma_f32_16x16x4_f32 v[244:247], v153, v221, v[244:247]
	v_mfma_f32_16x16x4_f32 v[72:75], v154, v222, v[72:75]
	v_mfma_f32_16x16x4_f32 v[244:247], v155, v223, v[244:247]
	s_nop 9
	v_pk_add_f32 v[72:73], v[72:73], v[244:245]
	v_pk_add_f32 v[74:75], v[74:75], v[246:247]
	v_fmac_f32_e32 v73, v156, v72
	v_pk_fma_f32 v[74:75], v[158:159], v[72:73], v[74:75] op_sel:[0,0,0] op_sel_hi:[1,0,1]
	v_pk_fma_f32 v[74:75], v[160:161], v[72:73], v[74:75] op_sel:[0,1,0] op_sel_hi:[1,1,1]
	v_fmac_f32_e32 v75, v157, v74
	ds_bpermute_b32 v204, v232, v72
	ds_bpermute_b32 v205, v232, v73
	ds_bpermute_b32 v206, v232, v74
	ds_bpermute_b32 v207, v232, v75
	ds_read_b128 v[140:143], v28 offset:9984
	ds_read_b128 v[144:147], v28 offset:10048
	ds_read_b128 v[148:151], v28 offset:10112
	ds_read_b128 v[152:155], v28 offset:10176
	s_waitcnt lgkmcnt(6)
	v_pk_fma_f32 v[72:73], v[162:163], v[204:205], v[72:73] op_sel:[0,0,0] op_sel_hi:[1,0,1]
	v_pk_fma_f32 v[72:73], v[164:165], v[204:205], v[72:73] op_sel:[0,1,0] op_sel_hi:[1,1,1]
	s_waitcnt lgkmcnt(4)
	v_pk_fma_f32 v[72:73], v[166:167], v[206:207], v[72:73] op_sel:[0,0,0] op_sel_hi:[1,0,1]
	v_pk_fma_f32 v[72:73], v[168:169], v[206:207], v[72:73] op_sel:[0,1,0] op_sel_hi:[1,1,1]
	v_pk_fma_f32 v[74:75], v[170:171], v[204:205], v[74:75] op_sel:[0,0,0] op_sel_hi:[1,0,1]
	v_pk_fma_f32 v[74:75], v[172:173], v[204:205], v[74:75] op_sel:[0,1,0] op_sel_hi:[1,1,1]
	v_pk_fma_f32 v[74:75], v[174:175], v[206:207], v[74:75] op_sel:[0,0,0] op_sel_hi:[1,0,1]
	v_pk_fma_f32 v[74:75], v[176:177], v[206:207], v[74:75] op_sel:[0,1,0] op_sel_hi:[1,1,1]
	v_fmac_f32_e32 v73, v178, v72
	v_pk_fma_f32 v[74:75], v[180:181], v[72:73], v[74:75] op_sel:[0,0,0] op_sel_hi:[1,0,1]
	v_pk_fma_f32 v[74:75], v[182:183], v[72:73], v[74:75] op_sel:[0,1,0] op_sel_hi:[1,1,1]
	v_fmac_f32_e32 v75, v179, v74
	v_cndmask_b32_e64 v200, v72, v136, s[98:99]
	v_cndmask_b32_e64 v201, v73, v137, s[98:99]
	v_cndmask_b32_e64 v202, v74, v138, s[98:99]
	v_cndmask_b32_e64 v203, v75, v139, s[98:99]
	v_cndmask_b32_e64 v252, v72, 0, s[98:99]
	v_cndmask_b32_e64 v253, v73, 0, s[98:99]
	v_cndmask_b32_e64 v254, v74, 0, s[98:99]
	v_cndmask_b32_e64 v255, v75, 0, s[98:99]
	v_mfma_f32_16x16x4_f32 v[208:211], v184, v200, v[208:211]
	v_mfma_f32_16x16x4_f32 v[212:215], v188, v200, v[212:215]
	v_mfma_f32_16x16x4_f32 v[216:219], v192, v200, v[216:219]
	v_mfma_f32_16x16x4_f32 v[220:223], v196, v200, v[220:223]
	v_mfma_f32_16x16x4_f32 v[208:211], v185, v201, v[208:211]
	v_mfma_f32_16x16x4_f32 v[212:215], v189, v201, v[212:215]
	v_mfma_f32_16x16x4_f32 v[216:219], v193, v201, v[216:219]
	v_mfma_f32_16x16x4_f32 v[220:223], v197, v201, v[220:223]
	v_mfma_f32_16x16x4_f32 v[208:211], v186, v202, v[208:211]
	v_mfma_f32_16x16x4_f32 v[212:215], v190, v202, v[212:215]
	v_mfma_f32_16x16x4_f32 v[216:219], v194, v202, v[216:219]
	v_mfma_f32_16x16x4_f32 v[220:223], v198, v202, v[220:223]
	v_mfma_f32_16x16x4_f32 v[208:211], v187, v203, v[208:211]
	v_mfma_f32_16x16x4_f32 v[212:215], v191, v203, v[212:215]
	v_mfma_f32_16x16x4_f32 v[216:219], v195, v203, v[216:219]
	v_mfma_f32_16x16x4_f32 v[220:223], v199, v203, v[220:223]
	v_mfma_f32_16x16x4_f32 v[248:251], v132, v252, v[72:75]
	v_mfma_f32_16x16x4_f32 v[248:251], v133, v253, v[248:251]
	v_mfma_f32_16x16x4_f32 v[248:251], v134, v254, v[248:251]
	v_mfma_f32_16x16x4_f32 v[248:251], v135, v255, v[248:251]
	s_waitcnt lgkmcnt(3)
	s_nop 2
	v_pk_mul_f32 v[208:209], v[208:209], v[140:141]
	v_pk_mul_f32 v[210:211], v[210:211], v[142:143]
	s_waitcnt lgkmcnt(2)
	v_pk_mul_f32 v[212:213], v[212:213], v[144:145]
	v_pk_mul_f32 v[214:215], v[214:215], v[146:147]
	s_waitcnt lgkmcnt(1)
	v_pk_mul_f32 v[216:217], v[216:217], v[148:149]
	v_pk_mul_f32 v[218:219], v[218:219], v[150:151]
	s_waitcnt lgkmcnt(0)
	v_pk_mul_f32 v[220:221], v[220:221], v[152:153]
	v_pk_mul_f32 v[222:223], v[222:223], v[154:155]
	s_mov_b64 exec, s[98:99]
	ds_write_b32 v231, v248 offset:6144
	ds_write_b32 v231, v249 offset:6400
	ds_write_b32 v231, v250 offset:6656
	ds_write_b32 v231, v251 offset:6912
	s_mov_b64 exec, -1
	s_branch .LBB0_655

.Lmy_f_hl2:
	s_bfe_u32 s100, s62, 0x20006
	s_lshl_b32 s100, s100, 2
	s_add_i32 s101, s100, -16
	s_add_i32 s100, s100, -12
	s_cmp_lg_u32 s65, 0
	s_cbranch_scc1 .Lmy_f_nol2
	v_add_u32_e32 v70, s101, v70
	v_subrev_u32_e32 v71, s101, v71
	v_add_u32_e32 v21, 64, v70
	v_subrev_u32_e32 v26, 64, v71
	v_cndmask_b32_e64 v32, v26, v21, s[4:5]
	v_ashrrev_i32_e32 v33, 31, v32
	v_lshl_add_u64 v[44:45], v[32:33], 0, s[40:41]
	v_mad_u64_u32 v[46:47], s[96:97], v44, s56, v[50:51]
	v_mad_i32_i24 v47, v45, s56, v47
	v_mov_b32_e32 v166, v46
	v_mov_b32_e32 v167, v47
	global_load_dwordx2 v[26:27], v[46:47], off
	v_mov_b32_e32 v30, v20
	v_mov_b32_e32 v31, v20
	v_cmp_lt_i32_e64 s[96:97], 0, v32
	v_mov_b64_e32 v[28:29], v[30:31]
	s_and_saveexec_b64 s[24:25], s[96:97]
	s_cbranch_execz .Lmy_f_k659
	v_add_co_u32_e32 v28, vcc, 0xfffff000, v46
	s_nop 1
	v_addc_co_u32_e32 v29, vcc, -1, v47, vcc
	global_load_dwordx2 v[28:29], v[28:29], off offset:-2048

.Lmy_f_k669:
	s_or_b64 exec, exec, s[96:97]
	v_lshlrev_b64 v[44:45], 13, v[44:45]
	v_lshl_add_u64 v[44:45], v[52:53], 0, v[44:45]
	v_mov_b32_e32 v170, v44
	v_mov_b32_e32 v171, v45
	v_add_co_u32_e32 v46, vcc, 0x1000, v44
	s_nop 1
	v_addc_co_u32_e32 v47, vcc, 0, v45, vcc
	global_load_dwordx2 v[44:45], v[44:45], off
	s_nop 0
	global_load_dwordx2 v[46:47], v[46:47], off
	v_subrev_u32_e32 v70, s101, v70
	v_add_u32_e32 v71, s101, v71
	v_add_u32_e32 v70, s100, v70
	v_subrev_u32_e32 v71, s100, v71
	v_add_u32_e32 v21, 64, v70
	v_subrev_u32_e32 v140, 64, v71
	v_cndmask_b32_e64 v146, v140, v21, s[4:5]
	v_ashrrev_i32_e32 v147, 31, v146
	v_lshl_add_u64 v[158:159], v[146:147], 0, s[40:41]
	v_mad_u64_u32 v[160:161], s[96:97], v158, s56, v[50:51]
	v_mad_i32_i24 v161, v159, s56, v161
	v_mov_b32_e32 v174, v160
	v_mov_b32_e32 v175, v161
	global_load_dwordx2 v[140:141], v[160:161], off
	v_mov_b32_e32 v144, v20
	v_mov_b32_e32 v145, v20
	v_cmp_lt_i32_e64 s[96:97], 0, v146
	v_mov_b64_e32 v[142:143], v[144:145]
	s_and_saveexec_b64 s[24:25], s[96:97]
	s_cbranch_execz .Lmy_f_l659
	v_add_co_u32_e32 v142, vcc, 0xfffff000, v160
	s_nop 1
	v_addc_co_u32_e32 v143, vcc, -1, v161, vcc
	global_load_dwordx2 v[142:143], v[142:143], off offset:-2048

.Lmy_f_l669:
	s_or_b64 exec, exec, s[96:97]
	v_lshlrev_b64 v[158:159], 13, v[158:159]
	v_lshl_add_u64 v[158:159], v[52:53], 0, v[158:159]
	v_mov_b32_e32 v178, v158
	v_mov_b32_e32 v179, v159
	v_add_co_u32_e32 v160, vcc, 0x1000, v158
	s_nop 1
	v_addc_co_u32_e32 v161, vcc, 0, v159, vcc
	global_load_dwordx2 v[158:159], v[158:159], off
	s_nop 0
	global_load_dwordx2 v[160:161], v[160:161], off
	v_subrev_u32_e32 v70, s100, v70
	v_add_u32_e32 v71, s100, v71
	s_mov_b32 s96, 0xffffe000
	s_mov_b32 s97, -1
	v_lshl_add_u64 v[164:165], v[166:167], 0, s[96:97]
	v_lshl_add_u64 v[172:173], v[174:175], 0, s[96:97]
	s_mov_b32 s96, 0x2000
	s_mov_b32 s97, 0
	v_lshl_add_u64 v[168:169], v[166:167], 0, s[96:97]
	v_lshl_add_u64 v[176:177], v[174:175], 0, s[96:97]
	s_mov_b32 s96, 0x800
	v_lshl_add_u64 v[170:171], v[170:171], 0, s[96:97]
	v_lshl_add_u64 v[178:179], v[178:179], 0, s[96:97]
.Lmy_f_nol2:
	s_lshl_b32 s96, s101, 8
	v_add_u32_e32 v67, s96, v67
	s_andn2_b64 vcc, exec, s[50:51]
	s_cbranch_vccnz .LBB0_655
	s_waitcnt vmcnt(15)
	v_lshlrev_b32_e32 v72, 16, v28
	v_and_b32_e32 v73, 0xffff0000, v28
	v_lshlrev_b32_e32 v76, 16, v30
	v_and_b32_e32 v77, 0xffff0000, v30
	v_lshlrev_b32_e32 v74, 16, v26
	v_and_b32_e32 v75, 0xffff0000, v26
	v_pk_add_f32 v[72:73], v[72:73], v[76:77]
	s_waitcnt vmcnt(13)
	v_lshlrev_b32_e32 v78, 16, v42
	v_pk_fma_f32 v[72:73], v[72:73], 0.5, v[74:75] op_sel_hi:[1,0,1] neg_lo:[0,0,1] neg_hi:[0,0,1]
	v_and_b32_e32 v79, 0xffff0000, v42
	v_pk_fma_f32 v[72:73], v[0:1], v[72:73], v[74:75]
	v_lshlrev_b32_e32 v74, 16, v40
	v_and_b32_e32 v75, 0xffff0000, v40
	v_lshlrev_b32_e32 v76, 16, v38
	v_and_b32_e32 v77, 0xffff0000, v38
	v_pk_add_f32 v[74:75], v[74:75], v[78:79]
	s_waitcnt vmcnt(12)
	v_cvt_f32_f16_e32 v21, v44
	v_pk_fma_f32 v[74:75], v[74:75], 0.5, v[76:77] op_sel_hi:[1,0,1] neg_lo:[0,0,1] neg_hi:[0,0,1]
	v_lshlrev_b32_e32 v80, 16, v31
	v_pk_fma_f32 v[76:77], v[8:9], v[74:75], v[76:77]
	v_lshlrev_b32_e32 v74, 16, v29
	v_and_b32_e32 v75, 0xffff0000, v29
	v_and_b32_e32 v81, 0xffff0000, v31
	v_lshlrev_b32_e32 v78, 16, v27
	v_and_b32_e32 v79, 0xffff0000, v27
	v_pk_add_f32 v[74:75], v[74:75], v[80:81]
	v_cvt_f32_f16_sdwa v84, v44 dst_sel:DWORD dst_unused:UNUSED_PAD src0_sel:WORD_1
	v_pk_fma_f32 v[74:75], v[74:75], 0.5, v[78:79] op_sel_hi:[1,0,1] neg_lo:[0,0,1] neg_hi:[0,0,1]
	v_lshlrev_b32_e32 v82, 16, v43
	v_pk_fma_f32 v[74:75], v[2:3], v[74:75], v[78:79]
	v_lshlrev_b32_e32 v78, 16, v41
	v_and_b32_e32 v79, 0xffff0000, v41
	v_and_b32_e32 v83, 0xffff0000, v43
	v_cvt_f32_f16_e32 v88, v45
	v_lshlrev_b32_e32 v80, 16, v39
	v_and_b32_e32 v81, 0xffff0000, v39
	v_pk_add_f32 v[78:79], v[78:79], v[82:83]
	v_mul_f32_e32 v21, 0xbf1b4598, v21
	v_pk_fma_f32 v[78:79], v[78:79], 0.5, v[80:81] op_sel_hi:[1,0,1] neg_lo:[0,0,1] neg_hi:[0,0,1]
	v_mul_f32_e32 v21, 0x3fb8aa3b, v21
	v_cvt_f32_f16_sdwa v89, v45 dst_sel:DWORD dst_unused:UNUSED_PAD src0_sel:WORD_1
	v_pk_fma_f32 v[78:79], v[10:11], v[78:79], v[80:81]
	v_exp_f32_e32 v80, v21
	v_mul_f32_e32 v21, 0xbf1b4598, v84
	v_mul_f32_e32 v21, 0x3fb8aa3b, v21
	v_lshlrev_b32_e32 v82, 16, v34
	v_and_b32_e32 v83, 0xffff0000, v34
	v_lshlrev_b32_e32 v86, 16, v36
	v_and_b32_e32 v87, 0xffff0000, v36
	v_exp_f32_e32 v81, v21
	v_lshlrev_b32_e32 v84, 16, v32
	v_and_b32_e32 v85, 0xffff0000, v32
	v_pk_add_f32 v[82:83], v[82:83], v[86:87]
	v_mul_f32_e32 v21, 0xbf1b4598, v88
	v_pk_fma_f32 v[82:83], v[82:83], 0.5, v[84:85] op_sel_hi:[1,0,1] neg_lo:[0,0,1] neg_hi:[0,0,1]
	v_mul_f32_e32 v21, 0x3fb8aa3b, v21
	v_pk_fma_f32 v[96:97], v[4:5], v[82:83], v[84:85]
	v_exp_f32_e32 v82, v21
	v_mul_f32_e32 v21, 0xbf1b4598, v89
	v_lshlrev_b32_e32 v84, 16, v35
	v_and_b32_e32 v85, 0xffff0000, v35
	v_lshlrev_b32_e32 v88, 16, v37
	v_and_b32_e32 v89, 0xffff0000, v37
	v_lshlrev_b32_e32 v86, 16, v33
	v_and_b32_e32 v87, 0xffff0000, v33
	v_pk_add_f32 v[84:85], v[84:85], v[88:89]
	s_waitcnt vmcnt(11)
	v_cvt_f32_f16_sdwa v93, v46 dst_sel:DWORD dst_unused:UNUSED_PAD src0_sel:WORD_1
	v_pk_fma_f32 v[84:85], v[84:85], 0.5, v[86:87] op_sel_hi:[1,0,1] neg_lo:[0,0,1] neg_hi:[0,0,1]
	v_cvt_f32_f16_e32 v92, v46
	v_pk_fma_f32 v[94:95], v[6:7], v[84:85], v[86:87]
	v_pk_mul_f32 v[84:85], v[12:13], v[96:97]
	v_pk_mul_f32 v[88:89], v[14:15], v[94:95]
	v_pk_mul_f32 v[86:87], v[84:85], v[84:85]
	v_pk_mul_f32 v[90:91], v[88:89], v[88:89]
	v_add_f32_e32 v83, v86, v87
	v_add_f32_e32 v83, v90, v83
	v_add_f32_e32 v83, v91, v83
	v_cvt_f32_f16_sdwa v99, v47 dst_sel:DWORD dst_unused:UNUSED_PAD src0_sel:WORD_1
	v_cvt_f32_f16_e32 v98, v47
	v_add_f32_dpp v83, v83, v83 quad_perm:[1,0,3,2] row_mask:0xf bank_mask:0xf bound_ctrl:1
	v_mul_f32_e32 v21, 0x3fb8aa3b, v21
	s_bitcmp1_b32 s22, 0
	v_add_f32_dpp v83, v83, v83 quad_perm:[2,3,0,1] row_mask:0xf bank_mask:0xf bound_ctrl:1
	s_cselect_b32 s23, 0x2000, 0
	s_nop 0
	v_add_f32_dpp v83, v83, v83 row_half_mirror row_mask:0xf bank_mask:0xf bound_ctrl:1
	s_nop 1
	v_add_f32_dpp v83, v83, v83 row_mirror row_mask:0xf bank_mask:0xf bound_ctrl:1
	v_max_f32_e32 v83, 0x179abe15, v83
	v_rsq_f32_e32 v86, v83
	v_exp_f32_e32 v83, v21
	v_add_u32_e32 v21, s23, v67
	v_pk_mul_f32 v[90:91], v[84:85], v[86:87] op_sel_hi:[1,0]
	v_pk_mul_f32 v[100:101], v[88:89], v[86:87] op_sel_hi:[1,0]
	v_xor_b32_e32 v85, 0x80000000, v91
	v_xor_b32_e32 v84, 0x80000000, v90
	v_pk_mul_f32 v[88:89], v[90:91], v[92:93]
	v_pk_mul_f32 v[90:91], v[100:101], v[98:99]
	v_pk_add_f32 v[92:93], v[92:93], -1.0 op_sel_hi:[1,0]
	v_pk_add_f32 v[98:99], v[98:99], -1.0 op_sel_hi:[1,0]
	v_pk_fma_f32 v[92:93], v[16:17], v[92:93], 1.0 op_sel_hi:[1,1,0]
	v_pk_fma_f32 v[98:99], v[18:19], v[98:99], 1.0 op_sel_hi:[1,1,0]
	v_xor_b32_e32 v86, 0x80000000, v100
	v_xor_b32_e32 v87, 0x80000000, v101
	v_pk_mul_f32 v[94:95], v[94:95], v[98:99]
	v_pk_mul_f32 v[92:93], v[96:97], v[92:93]
	ds_write_b128 v67, v[80:83]
	ds_write_b128 v67, v[84:87] offset:8192
	ds_write_b128 v67, v[88:91] offset:16384
	ds_write_b128 v67, v[92:95] offset:24576
	ds_write_b128 v67, v[72:75] offset:32768
	ds_write_b128 v21, v[76:79] offset:40960
	v_add_u32_e32 v67, 0x400, v67
	s_waitcnt vmcnt(0)
	v_lshlrev_b32_e32 v72, 16, v142
	v_and_b32_e32 v73, 0xffff0000, v142
	v_lshlrev_b32_e32 v76, 16, v144
	v_and_b32_e32 v77, 0xffff0000, v144
	v_lshlrev_b32_e32 v74, 16, v140
	v_and_b32_e32 v75, 0xffff0000, v140
	v_pk_add_f32 v[72:73], v[72:73], v[76:77]
	s_waitcnt vmcnt(2)
	v_lshlrev_b32_e32 v78, 16, v156
	v_pk_fma_f32 v[72:73], v[72:73], 0.5, v[74:75] op_sel_hi:[1,0,1] neg_lo:[0,0,1] neg_hi:[0,0,1]
	v_and_b32_e32 v79, 0xffff0000, v156
	v_pk_fma_f32 v[72:73], v[0:1], v[72:73], v[74:75]
	v_lshlrev_b32_e32 v74, 16, v154
	v_and_b32_e32 v75, 0xffff0000, v154
	v_lshlrev_b32_e32 v76, 16, v152
	v_and_b32_e32 v77, 0xffff0000, v152
	v_pk_add_f32 v[74:75], v[74:75], v[78:79]
	s_waitcnt vmcnt(1)
	v_cvt_f32_f16_e32 v21, v158
	v_pk_fma_f32 v[74:75], v[74:75], 0.5, v[76:77] op_sel_hi:[1,0,1] neg_lo:[0,0,1] neg_hi:[0,0,1]
	v_lshlrev_b32_e32 v80, 16, v145
	v_pk_fma_f32 v[76:77], v[8:9], v[74:75], v[76:77]
	v_lshlrev_b32_e32 v74, 16, v143
	v_and_b32_e32 v75, 0xffff0000, v143
	v_and_b32_e32 v81, 0xffff0000, v145
	v_lshlrev_b32_e32 v78, 16, v141
	v_and_b32_e32 v79, 0xffff0000, v141
	v_pk_add_f32 v[74:75], v[74:75], v[80:81]
	v_cvt_f32_f16_sdwa v84, v158 dst_sel:DWORD dst_unused:UNUSED_PAD src0_sel:WORD_1
	v_pk_fma_f32 v[74:75], v[74:75], 0.5, v[78:79] op_sel_hi:[1,0,1] neg_lo:[0,0,1] neg_hi:[0,0,1]
	v_lshlrev_b32_e32 v82, 16, v157
	v_pk_fma_f32 v[74:75], v[2:3], v[74:75], v[78:79]
	v_lshlrev_b32_e32 v78, 16, v155
	v_and_b32_e32 v79, 0xffff0000, v155
	v_and_b32_e32 v83, 0xffff0000, v157
	v_cvt_f32_f16_e32 v88, v159
	v_lshlrev_b32_e32 v80, 16, v153
	v_and_b32_e32 v81, 0xffff0000, v153
	v_pk_add_f32 v[78:79], v[78:79], v[82:83]
	v_mul_f32_e32 v21, 0xbf1b4598, v21
	v_pk_fma_f32 v[78:79], v[78:79], 0.5, v[80:81] op_sel_hi:[1,0,1] neg_lo:[0,0,1] neg_hi:[0,0,1]
	v_mul_f32_e32 v21, 0x3fb8aa3b, v21
	v_cvt_f32_f16_sdwa v89, v159 dst_sel:DWORD dst_unused:UNUSED_PAD src0_sel:WORD_1
	v_pk_fma_f32 v[78:79], v[10:11], v[78:79], v[80:81]
	v_exp_f32_e32 v80, v21
	v_mul_f32_e32 v21, 0xbf1b4598, v84
	v_mul_f32_e32 v21, 0x3fb8aa3b, v21
	v_lshlrev_b32_e32 v82, 16, v148
	v_and_b32_e32 v83, 0xffff0000, v148
	v_lshlrev_b32_e32 v86, 16, v150
	v_and_b32_e32 v87, 0xffff0000, v150
	v_exp_f32_e32 v81, v21
	v_lshlrev_b32_e32 v84, 16, v146
	v_and_b32_e32 v85, 0xffff0000, v146
	v_pk_add_f32 v[82:83], v[82:83], v[86:87]
	v_mul_f32_e32 v21, 0xbf1b4598, v88
	v_pk_fma_f32 v[82:83], v[82:83], 0.5, v[84:85] op_sel_hi:[1,0,1] neg_lo:[0,0,1] neg_hi:[0,0,1]
	v_mul_f32_e32 v21, 0x3fb8aa3b, v21
	v_pk_fma_f32 v[96:97], v[4:5], v[82:83], v[84:85]
	v_exp_f32_e32 v82, v21
	v_mul_f32_e32 v21, 0xbf1b4598, v89
	v_lshlrev_b32_e32 v84, 16, v149
	v_and_b32_e32 v85, 0xffff0000, v149
	v_lshlrev_b32_e32 v88, 16, v151
	v_and_b32_e32 v89, 0xffff0000, v151
	v_lshlrev_b32_e32 v86, 16, v147
	v_and_b32_e32 v87, 0xffff0000, v147
	v_pk_add_f32 v[84:85], v[84:85], v[88:89]
	s_waitcnt vmcnt(0)
	v_cvt_f32_f16_sdwa v93, v160 dst_sel:DWORD dst_unused:UNUSED_PAD src0_sel:WORD_1
	v_pk_fma_f32 v[84:85], v[84:85], 0.5, v[86:87] op_sel_hi:[1,0,1] neg_lo:[0,0,1] neg_hi:[0,0,1]
	v_cvt_f32_f16_e32 v92, v160
	v_pk_fma_f32 v[94:95], v[6:7], v[84:85], v[86:87]
	v_pk_mul_f32 v[84:85], v[12:13], v[96:97]
	v_pk_mul_f32 v[88:89], v[14:15], v[94:95]
	v_pk_mul_f32 v[86:87], v[84:85], v[84:85]
	v_pk_mul_f32 v[90:91], v[88:89], v[88:89]
	v_add_f32_e32 v83, v86, v87
	v_add_f32_e32 v83, v90, v83
	v_add_f32_e32 v83, v91, v83
	v_cvt_f32_f16_sdwa v99, v161 dst_sel:DWORD dst_unused:UNUSED_PAD src0_sel:WORD_1
	v_cvt_f32_f16_e32 v98, v161
	v_add_f32_dpp v83, v83, v83 quad_perm:[1,0,3,2] row_mask:0xf bank_mask:0xf bound_ctrl:1
	v_mul_f32_e32 v21, 0x3fb8aa3b, v21
	s_bitcmp1_b32 s22, 0
	v_add_f32_dpp v83, v83, v83 quad_perm:[2,3,0,1] row_mask:0xf bank_mask:0xf bound_ctrl:1
	s_cselect_b32 s23, 0x2000, 0
	s_nop 0
	v_add_f32_dpp v83, v83, v83 row_half_mirror row_mask:0xf bank_mask:0xf bound_ctrl:1
	s_nop 1
	v_add_f32_dpp v83, v83, v83 row_mirror row_mask:0xf bank_mask:0xf bound_ctrl:1
	v_max_f32_e32 v83, 0x179abe15, v83
	v_rsq_f32_e32 v86, v83
	v_exp_f32_e32 v83, v21
	v_add_u32_e32 v21, s23, v67
	v_pk_mul_f32 v[90:91], v[84:85], v[86:87] op_sel_hi:[1,0]
	v_pk_mul_f32 v[100:101], v[88:89], v[86:87] op_sel_hi:[1,0]
	v_xor_b32_e32 v85, 0x80000000, v91
	v_xor_b32_e32 v84, 0x80000000, v90
	v_pk_mul_f32 v[88:89], v[90:91], v[92:93]
	v_pk_mul_f32 v[90:91], v[100:101], v[98:99]
	v_pk_add_f32 v[92:93], v[92:93], -1.0 op_sel_hi:[1,0]
	v_pk_add_f32 v[98:99], v[98:99], -1.0 op_sel_hi:[1,0]
	v_pk_fma_f32 v[92:93], v[16:17], v[92:93], 1.0 op_sel_hi:[1,1,0]
	v_pk_fma_f32 v[98:99], v[18:19], v[98:99], 1.0 op_sel_hi:[1,1,0]
	v_xor_b32_e32 v86, 0x80000000, v100
	v_xor_b32_e32 v87, 0x80000000, v101
	v_pk_mul_f32 v[94:95], v[94:95], v[98:99]
	v_pk_mul_f32 v[92:93], v[96:97], v[92:93]
	ds_write_b128 v67, v[80:83]
	ds_write_b128 v67, v[84:87] offset:8192
	ds_write_b128 v67, v[88:91] offset:16384
	ds_write_b128 v67, v[92:95] offset:24576
	ds_write_b128 v67, v[72:75] offset:32768
	ds_write_b128 v21, v[76:79] offset:40960
	s_lshl_b32 s96, s100, 8
	v_subrev_u32_e32 v67, s96, v67
	s_cmp_gt_u32 s65, 61
	s_cbranch_scc1 .Lmy_f_nol34
	s_cmp_eq_u32 s65, 61
	s_cbranch_scc1 .Lmy_f_slow34
	s_cmp_lg_u32 s4, 0
	s_mov_b32 s100, 0xfffd0000
	s_cselect_b32 s100, 0x30000, s100
	s_cselect_b32 s101, 0, -1
	s_mov_b32 s96, 0xfffc0000
	s_cselect_b32 s96, 0x40000, s96
	s_cselect_b32 s97, 0, -1
	v_lshl_add_u64 v[166:167], v[166:167], 0, s[100:101]
	v_lshl_add_u64 v[164:165], v[164:165], 0, s[100:101]
	v_lshl_add_u64 v[168:169], v[168:169], 0, s[100:101]
	v_lshl_add_u64 v[170:171], v[170:171], 0, s[96:97]
	global_load_dwordx2 v[26:27], v[166:167], off
	global_load_dwordx2 v[28:29], v[164:165], off offset:2048
	global_load_dwordx2 v[30:31], v[168:169], off offset:-2048
	global_load_dwordx2 v[32:33], v[166:167], off offset:2048
	global_load_dwordx2 v[34:35], v[166:167], off offset:-4096
	global_load_dwordx2 v[36:37], v[168:169], off
	global_load_dwordx2 v[38:39], v[168:169], off offset:-4096
	global_load_dwordx2 v[40:41], v[166:167], off offset:-2048
	global_load_dwordx2 v[42:43], v[168:169], off offset:2048
	global_load_dwordx2 v[44:45], v[170:171], off offset:-2048
	global_load_dwordx2 v[46:47], v[170:171], off offset:2048
	v_lshl_add_u64 v[174:175], v[174:175], 0, s[100:101]
	v_lshl_add_u64 v[172:173], v[172:173], 0, s[100:101]
	v_lshl_add_u64 v[176:177], v[176:177], 0, s[100:101]
	v_lshl_add_u64 v[178:179], v[178:179], 0, s[96:97]
	global_load_dwordx2 v[140:141], v[174:175], off
	global_load_dwordx2 v[142:143], v[172:173], off offset:2048
	global_load_dwordx2 v[144:145], v[176:177], off offset:-2048
	global_load_dwordx2 v[146:147], v[174:175], off offset:2048
	global_load_dwordx2 v[148:149], v[174:175], off offset:-4096
	global_load_dwordx2 v[150:151], v[176:177], off
	global_load_dwordx2 v[152:153], v[176:177], off offset:-4096
	global_load_dwordx2 v[154:155], v[174:175], off offset:-2048
	global_load_dwordx2 v[156:157], v[176:177], off offset:2048
	global_load_dwordx2 v[158:159], v[178:179], off offset:-2048
	global_load_dwordx2 v[160:161], v[178:179], off offset:2048
	s_branch .Lmy_f_nol34
.Lmy_f_slow34:
	s_add_i32 s101, s101, 32
	s_add_i32 s100, s100, 32
	v_add_u32_e32 v70, s101, v70
	v_subrev_u32_e32 v71, s101, v71
	v_add_u32_e32 v21, 64, v70
	v_subrev_u32_e32 v26, 64, v71
	v_cndmask_b32_e64 v32, v26, v21, s[4:5]
	v_ashrrev_i32_e32 v33, 31, v32
	v_lshl_add_u64 v[44:45], v[32:33], 0, s[40:41]
	v_mad_u64_u32 v[46:47], s[96:97], v44, s56, v[50:51]
	v_mad_i32_i24 v47, v45, s56, v47
	global_load_dwordx2 v[26:27], v[46:47], off
	v_mov_b32_e32 v30, v20
	v_mov_b32_e32 v31, v20
	v_cmp_lt_i32_e64 s[96:97], 0, v32
	v_mov_b64_e32 v[28:29], v[30:31]
	s_and_saveexec_b64 s[24:25], s[96:97]
	s_cbranch_execz .Lmy_f_m659
	v_add_co_u32_e32 v28, vcc, 0xfffff000, v46
	s_nop 1
	v_addc_co_u32_e32 v29, vcc, -1, v47, vcc
	global_load_dwordx2 v[28:29], v[28:29], off offset:-2048
